# v5 + w_down conversion in the gate/up tail paced (s_sleep 64 per item)
# speedup vs baseline: 1.0133x; 1.0133x over previous
; __device__ __forceinline__ void convert_items(KArgs A, unsigned char* ws, LAS unsigned char* lds, int it0, int it1, int gw, int NGW, int wave, int lane) {
;     ...
; #pragma nounroll
;     for (int it = it0 + gw; it < it1; it += NGW) {
;         int r = it;
;         if (r < CI_IN) { const int kb = r / 112, nb = r % 112, pn = nb >> 3, cbk = nb & 7; const float* g1 = A->in.g1;
;             p0_transpose_item(A->in.win, DM, NIN, WIN, kb, nb, 256 * pn + 128 * (cbk & 1) + 32 * (cbk >> 1), scr, lane, [g1](int k) { return g1[k]; }); continue; } r -= CI_IN;
;         if (r < CI_OUT) { const int kb = r / 32, nb = r % 32; const float* sg = A->in.subg; const float* og = A->in.ong;
;             p0_transpose_item(A->in.wout, DM, DM, WOUT, kb, nb, 32 * nb, scr, lane, [sg, og](int k) { return k < 512 ? 0.8f * sg[k & 127] : og[k & 127]; }); continue; } r -= CI_OUT;
;         if (r < CI_G) { const int kb = r / 88, nb = r % 88; const float* g2 = A->in.g2;
;             p0_transpose_item(A->in.wg, DM, DFF, WGU, kb, nb, 256 * (nb >> 2) + 32 * (nb & 3), scr, lane, [g2](int k) { return g2[k]; }); continue; } r -= CI_G;
;         if (r < CI_G) { const int kb = r / 88, nb = r % 88; const float* g2 = A->in.g2;
;             p0_transpose_item(A->in.wu, DM, DFF, WGU, kb, nb, 256 * (nb >> 2) + 128 + 32 * (nb & 3), scr, lane, [g2](int k) { return g2[k]; }); continue; } r -= CI_G;
;         { const int kb = r / 32, nb = r % 32; p0_transpose_item(A->in.wd, DFF, DM, WDN, kb, nb, 32 * nb, scr, lane, [](int) { return 1.0f; }); }
.LBB0_1035:
	s_sleep 64
	s_cmpk_gt_i32 s35, 0x6ff
	s_mov_b64 s[4:5], -1
	s_cbranch_scc0 .LBB0_1093
	s_lshr_b32 s22, s41, 6
	s_cmpk_gt_u32 s35, 0x8ff
	s_cbranch_scc0 .LBB0_1056
	s_cmpk_gt_u32 s35, 0xe7f
	s_cbranch_scc0 .LBB0_1051
	s_cmpk_gt_u32 s35, 0x13ff
	s_cbranch_scc0 .LBB0_1046
	s_mul_i32 s4, s37, s40
	s_add_i32 s4, s36, s4
	s_andn2_b32 s4, s4, 63
	v_add_u32_e32 v29, s4, v55
	s_load_dwordx2 s[4:5], s[14:15], 0xa8
	s_lshl_b32 s6, s35, 5
	s_lshl_b32 s7, s35, 1
	s_and_b32 s6, s6, 0x3e0
	s_andn2_b32 s7, s7, 63
	s_add_i32 s18, s7, 0xffffd800
	s_lshl_b32 s7, s6, 2
	s_waitcnt lgkmcnt(0)
	s_add_u32 s4, s4, s7
	s_addc_u32 s5, s5, 0
	v_lshl_add_u64 v[32:33], s[4:5], 0, v[2:3]
	v_cmp_gt_i32_e32 vcc, s3, v29
	s_and_saveexec_b64 s[4:5], vcc
	s_xor_b64 s[4:5], exec, s[4:5]
	s_cbranch_execz .LBB0_1042
	v_add_u32_e32 v29, s18, v1
	v_add_u32_e32 v34, s18, v4
	v_add_u32_e32 v31, s18, v5
	v_add_u32_e32 v36, s18, v18
	v_add_u32_e32 v35, s18, v9
	v_add_u32_e32 v38, s18, v20
	v_add_u32_e32 v37, s18, v19
	v_add_u32_e32 v40, s18, v22
	v_add_u32_e32 v39, s18, v21
	v_add_u32_e32 v42, s18, v24
	v_add_u32_e32 v41, s18, v23
	v_add_u32_e32 v44, s18, v26
	v_add_u32_e32 v43, s18, v25
	v_add_u32_e32 v46, s18, v28
	v_add_u32_e32 v45, s18, v27
	v_add_u32_e32 v48, s18, v30
	s_mov_b32 s7, 1
	s_mov_b32 s23, 0
	s_mov_b32 s26, 32
